# grid barrier: non-leader workgroups poll the cross-XCD release word TOPGEN directly (one hop less); on top of v75
# baseline (speedup 1.0000x reference)
.LBB0_152:
	s_or_b64 exec, exec, s[10:11]
	v_cvt_f32_u32_e32 v4, v2
	s_waitcnt vmcnt(0)
	v_readfirstlane_b32 s8, v3
	v_sub_u32_e32 v3, 0, v2
	v_rcp_iflag_f32_e32 v4, v4
	v_add_u32_e32 v5, s8, v1
	v_mul_f32_e32 v4, 0x4f7ffffe, v4
	v_cvt_u32_f32_e32 v4, v4
	v_mul_lo_u32 v1, v3, v4
	v_mul_hi_u32 v1, v4, v1
	v_add_u32_e32 v1, v4, v1
	v_mul_hi_u32 v1, v5, v1
	v_mul_lo_u32 v3, v1, v2
	v_sub_u32_e32 v3, v5, v3
	v_add_u32_e32 v4, 1, v1
	v_cmp_ge_u32_e32 vcc, v3, v2
	s_nop 1
	v_cndmask_b32_e32 v1, v1, v4, vcc
	v_sub_u32_e32 v4, v3, v2
	v_cndmask_b32_e32 v3, v3, v4, vcc
	v_add_u32_e32 v4, 1, v1
	v_cmp_ge_u32_e32 vcc, v3, v2
	v_add_u32_e32 v3, 1, v5
	s_nop 0
	v_cndmask_b32_e32 v1, v1, v4, vcc
	v_mul_lo_u32 v4, v2, v1
	v_add_u32_e32 v2, v4, v2
	v_cmp_ne_u32_e32 vcc, v3, v2
	s_and_saveexec_b64 s[8:9], vcc
	s_xor_b64 s[8:9], exec, s[8:9]
	s_cbranch_execz .LBB0_166
	s_waitcnt lgkmcnt(0)
	buffer_inv sc1
	v_mov_b32_e32 v0, 0x7500
	global_load_dword v0, v0, s[40:41] sc1
	s_add_u32 s22, s40, 0x7500
	s_addc_u32 s23, s41, 0
	s_waitcnt vmcnt(0)
	v_cmp_eq_u32_e32 vcc, v0, v1
	s_and_saveexec_b64 s[10:11], vcc
	s_cbranch_execz .LBB0_165
	s_add_u32 s20, s40, 0x4200
	s_addc_u32 s21, s41, 0
	s_mov_b32 s26, 1
	s_mov_b64 s[24:25], 0
	v_mov_b32_e32 v0, 0
	s_branch .LBB0_156

.LBB0_361:
	s_or_b64 exec, exec, s[10:11]
	v_cvt_f32_u32_e32 v4, v2
	s_waitcnt vmcnt(0)
	v_readfirstlane_b32 s8, v3
	v_sub_u32_e32 v3, 0, v2
	v_rcp_iflag_f32_e32 v4, v4
	v_add_u32_e32 v5, s8, v1
	v_mul_f32_e32 v4, 0x4f7ffffe, v4
	v_cvt_u32_f32_e32 v4, v4
	v_mul_lo_u32 v1, v3, v4
	v_mul_hi_u32 v1, v4, v1
	v_add_u32_e32 v1, v4, v1
	v_mul_hi_u32 v1, v5, v1
	v_mul_lo_u32 v3, v1, v2
	v_sub_u32_e32 v3, v5, v3
	v_add_u32_e32 v4, 1, v1
	v_cmp_ge_u32_e32 vcc, v3, v2
	s_nop 1
	v_cndmask_b32_e32 v1, v1, v4, vcc
	v_sub_u32_e32 v4, v3, v2
	v_cndmask_b32_e32 v3, v3, v4, vcc
	v_add_u32_e32 v4, 1, v1
	v_cmp_ge_u32_e32 vcc, v3, v2
	v_add_u32_e32 v3, 1, v5
	s_nop 0
	v_cndmask_b32_e32 v1, v1, v4, vcc
	v_mul_lo_u32 v4, v2, v1
	v_add_u32_e32 v2, v4, v2
	v_cmp_ne_u32_e32 vcc, v3, v2
	s_and_saveexec_b64 s[8:9], vcc
	s_xor_b64 s[8:9], exec, s[8:9]
	s_cbranch_execz .LBB0_375
	s_waitcnt lgkmcnt(0)
	buffer_inv sc1
	v_mov_b32_e32 v0, 0x7500
	global_load_dword v0, v0, s[40:41] sc1
	s_add_u32 s16, s40, 0x7500
	s_addc_u32 s17, s41, 0
	s_waitcnt vmcnt(0)
	v_cmp_eq_u32_e32 vcc, v0, v1
	s_and_saveexec_b64 s[10:11], vcc
	s_cbranch_execz .LBB0_374
	s_add_u32 s14, s40, 0x4200
	s_addc_u32 s15, s41, 0
	s_mov_b32 s26, 1
	s_mov_b64 s[18:19], 0
	v_mov_b32_e32 v0, 0
	s_branch .LBB0_365

.LBB0_639:
	s_or_b64 exec, exec, s[10:11]
	v_cvt_f32_u32_e32 v4, v2
	s_waitcnt vmcnt(0)
	v_readfirstlane_b32 s8, v3
	v_sub_u32_e32 v3, 0, v2
	v_rcp_iflag_f32_e32 v4, v4
	v_add_u32_e32 v5, s8, v1
	v_mul_f32_e32 v4, 0x4f7ffffe, v4
	v_cvt_u32_f32_e32 v4, v4
	v_mul_lo_u32 v1, v3, v4
	v_mul_hi_u32 v1, v4, v1
	v_add_u32_e32 v1, v4, v1
	v_mul_hi_u32 v1, v5, v1
	v_mul_lo_u32 v3, v1, v2
	v_sub_u32_e32 v3, v5, v3
	v_add_u32_e32 v4, 1, v1
	v_cmp_ge_u32_e32 vcc, v3, v2
	s_nop 1
	v_cndmask_b32_e32 v1, v1, v4, vcc
	v_sub_u32_e32 v4, v3, v2
	v_cndmask_b32_e32 v3, v3, v4, vcc
	v_add_u32_e32 v4, 1, v1
	v_cmp_ge_u32_e32 vcc, v3, v2
	v_add_u32_e32 v3, 1, v5
	s_nop 0
	v_cndmask_b32_e32 v1, v1, v4, vcc
	v_mul_lo_u32 v4, v2, v1
	v_add_u32_e32 v2, v4, v2
	v_cmp_ne_u32_e32 vcc, v3, v2
	s_and_saveexec_b64 s[8:9], vcc
	s_xor_b64 s[8:9], exec, s[8:9]
	s_cbranch_execz .LBB0_653
	s_waitcnt lgkmcnt(0)
	buffer_inv sc1
	v_mov_b32_e32 v0, 0x7500
	global_load_dword v0, v0, s[40:41] sc1
	s_add_u32 s16, s40, 0x7500
	s_addc_u32 s17, s41, 0
	s_waitcnt vmcnt(0)
	v_cmp_eq_u32_e32 vcc, v0, v1
	s_and_saveexec_b64 s[10:11], vcc
	s_cbranch_execz .LBB0_652
	s_add_u32 s12, s40, 0x4200
	s_addc_u32 s13, s41, 0
	s_mov_b32 s26, 1
	s_mov_b64 s[18:19], 0
	v_mov_b32_e32 v0, 0
	s_branch .LBB0_643

.LBB0_747:
	s_or_b64 exec, exec, s[10:11]
	v_cvt_f32_u32_e32 v4, v2
	s_waitcnt vmcnt(0)
	v_readfirstlane_b32 s8, v3
	v_sub_u32_e32 v3, 0, v2
	v_rcp_iflag_f32_e32 v4, v4
	v_add_u32_e32 v5, s8, v1
	v_mul_f32_e32 v4, 0x4f7ffffe, v4
	v_cvt_u32_f32_e32 v4, v4
	v_mul_lo_u32 v1, v3, v4
	v_mul_hi_u32 v1, v4, v1
	v_add_u32_e32 v1, v4, v1
	v_mul_hi_u32 v1, v5, v1
	v_mul_lo_u32 v3, v1, v2
	v_sub_u32_e32 v3, v5, v3
	v_add_u32_e32 v4, 1, v1
	v_cmp_ge_u32_e32 vcc, v3, v2
	s_nop 1
	v_cndmask_b32_e32 v1, v1, v4, vcc
	v_sub_u32_e32 v4, v3, v2
	v_cndmask_b32_e32 v3, v3, v4, vcc
	v_add_u32_e32 v4, 1, v1
	v_cmp_ge_u32_e32 vcc, v3, v2
	v_add_u32_e32 v3, 1, v5
	s_nop 0
	v_cndmask_b32_e32 v1, v1, v4, vcc
	v_mul_lo_u32 v4, v2, v1
	v_add_u32_e32 v2, v4, v2
	v_cmp_ne_u32_e32 vcc, v3, v2
	s_and_saveexec_b64 s[8:9], vcc
	s_xor_b64 s[8:9], exec, s[8:9]
	s_cbranch_execz .LBB0_761
	s_waitcnt lgkmcnt(0)
	buffer_inv sc1
	v_mov_b32_e32 v0, 0x7500
	global_load_dword v0, v0, s[40:41] sc1
	s_add_u32 s14, s40, 0x7500
	s_addc_u32 s15, s41, 0
	s_waitcnt vmcnt(0)
	v_cmp_eq_u32_e32 vcc, v0, v1
	s_and_saveexec_b64 s[10:11], vcc
	s_cbranch_execz .LBB0_760
	s_add_u32 s12, s40, 0x4200
	s_addc_u32 s13, s41, 0
	s_mov_b32 s26, 1
	s_mov_b64 s[16:17], 0
	v_mov_b32_e32 v0, 0
	s_branch .LBB0_751

.LBB0_886:
	s_or_b64 exec, exec, s[12:13]
	v_cvt_f32_u32_e32 v38, v36
	s_waitcnt vmcnt(0)
	v_readfirstlane_b32 s10, v37
	v_sub_u32_e32 v37, 0, v36
	v_rcp_iflag_f32_e32 v38, v38
	v_add_u32_e32 v39, s10, v33
	v_mul_f32_e32 v38, 0x4f7ffffe, v38
	v_cvt_u32_f32_e32 v38, v38
	v_mul_lo_u32 v33, v37, v38
	v_mul_hi_u32 v33, v38, v33
	v_add_u32_e32 v33, v38, v33
	v_mul_hi_u32 v33, v39, v33
	v_mul_lo_u32 v37, v33, v36
	v_sub_u32_e32 v37, v39, v37
	v_add_u32_e32 v38, 1, v33
	v_cmp_ge_u32_e32 vcc, v37, v36
	s_nop 1
	v_cndmask_b32_e32 v33, v33, v38, vcc
	v_sub_u32_e32 v38, v37, v36
	v_cndmask_b32_e32 v37, v37, v38, vcc
	v_add_u32_e32 v38, 1, v33
	v_cmp_ge_u32_e32 vcc, v37, v36
	v_add_u32_e32 v37, 1, v39
	s_nop 0
	v_cndmask_b32_e32 v33, v33, v38, vcc
	v_mul_lo_u32 v38, v36, v33
	v_add_u32_e32 v36, v38, v36
	v_cmp_ne_u32_e32 vcc, v37, v36
	s_and_saveexec_b64 s[10:11], vcc
	s_xor_b64 s[10:11], exec, s[10:11]
	s_cbranch_execz .LBB0_900
	s_waitcnt lgkmcnt(0)
	buffer_inv sc1
	v_mov_b32_e32 v32, 0x7500
	global_load_dword v32, v32, s[40:41] sc1
	s_add_u32 s16, s40, 0x7500
	s_addc_u32 s17, s41, 0
	s_waitcnt vmcnt(0)
	v_cmp_eq_u32_e32 vcc, v32, v33
	s_and_saveexec_b64 s[12:13], vcc
	s_cbranch_execz .LBB0_899
	s_add_u32 s14, s40, 0x4200
	s_addc_u32 s15, s41, 0
	s_mov_b32 s28, 1
	s_mov_b64 s[18:19], 0
	v_mov_b32_e32 v32, 0
	s_branch .LBB0_890

.LBB0_972:
	s_or_b64 exec, exec, s[12:13]
	v_cvt_f32_u32_e32 v4, v2
	s_waitcnt vmcnt(0)
	v_readfirstlane_b32 s8, v3
	v_sub_u32_e32 v3, 0, v2
	v_rcp_iflag_f32_e32 v4, v4
	v_add_u32_e32 v5, s8, v1
	v_mul_f32_e32 v4, 0x4f7ffffe, v4
	v_cvt_u32_f32_e32 v4, v4
	v_mul_lo_u32 v1, v3, v4
	v_mul_hi_u32 v1, v4, v1
	v_add_u32_e32 v1, v4, v1
	v_mul_hi_u32 v1, v5, v1
	v_mul_lo_u32 v3, v1, v2
	v_sub_u32_e32 v3, v5, v3
	v_add_u32_e32 v4, 1, v1
	v_cmp_ge_u32_e32 vcc, v3, v2
	s_nop 1
	v_cndmask_b32_e32 v1, v1, v4, vcc
	v_sub_u32_e32 v4, v3, v2
	v_cndmask_b32_e32 v3, v3, v4, vcc
	v_add_u32_e32 v4, 1, v1
	v_cmp_ge_u32_e32 vcc, v3, v2
	v_add_u32_e32 v3, 1, v5
	s_nop 0
	v_cndmask_b32_e32 v1, v1, v4, vcc
	v_mul_lo_u32 v4, v2, v1
	v_add_u32_e32 v2, v4, v2
	v_cmp_ne_u32_e32 vcc, v3, v2
	s_and_saveexec_b64 s[8:9], vcc
	s_xor_b64 s[8:9], exec, s[8:9]
	s_cbranch_execz .LBB0_986
	s_waitcnt lgkmcnt(0)
	buffer_inv sc1
	v_mov_b32_e32 v0, 0x7500
	global_load_dword v0, v0, s[40:41] sc1
	s_add_u32 s16, s40, 0x7500
	s_addc_u32 s17, s41, 0
	s_waitcnt vmcnt(0)
	v_cmp_eq_u32_e32 vcc, v0, v1
	s_and_saveexec_b64 s[12:13], vcc
	s_cbranch_execz .LBB0_985
	s_add_u32 s14, s40, 0x4200
	s_addc_u32 s15, s41, 0
	s_mov_b32 s28, 1
	s_mov_b64 s[18:19], 0
	v_mov_b32_e32 v0, 0
	s_branch .LBB0_976

.LBB0_1078:
	s_or_b64 exec, exec, s[14:15]
	v_cvt_f32_u32_e32 v4, v2
	s_waitcnt vmcnt(0)
	v_readfirstlane_b32 s12, v3
	v_sub_u32_e32 v3, 0, v2
	v_rcp_iflag_f32_e32 v4, v4
	v_add_u32_e32 v5, s12, v1
	v_mul_f32_e32 v4, 0x4f7ffffe, v4
	v_cvt_u32_f32_e32 v4, v4
	v_mul_lo_u32 v1, v3, v4
	v_mul_hi_u32 v1, v4, v1
	v_add_u32_e32 v1, v4, v1
	v_mul_hi_u32 v1, v5, v1
	v_mul_lo_u32 v3, v1, v2
	v_sub_u32_e32 v3, v5, v3
	v_add_u32_e32 v4, 1, v1
	v_cmp_ge_u32_e32 vcc, v3, v2
	s_nop 1
	v_cndmask_b32_e32 v1, v1, v4, vcc
	v_sub_u32_e32 v4, v3, v2
	v_cndmask_b32_e32 v3, v3, v4, vcc
	v_add_u32_e32 v4, 1, v1
	v_cmp_ge_u32_e32 vcc, v3, v2
	v_add_u32_e32 v3, 1, v5
	s_nop 0
	v_cndmask_b32_e32 v1, v1, v4, vcc
	v_mul_lo_u32 v4, v2, v1
	v_add_u32_e32 v2, v4, v2
	v_cmp_ne_u32_e32 vcc, v3, v2
	s_and_saveexec_b64 s[12:13], vcc
	s_xor_b64 s[12:13], exec, s[12:13]
	s_cbranch_execz .LBB0_1092
	s_waitcnt lgkmcnt(0)
	buffer_inv sc1
	v_mov_b32_e32 v0, 0x7500
	global_load_dword v0, v0, s[40:41] sc1
	s_add_u32 s20, s40, 0x7500
	s_addc_u32 s21, s41, 0
	s_waitcnt vmcnt(0)
	v_cmp_eq_u32_e32 vcc, v0, v1
	s_and_saveexec_b64 s[14:15], vcc
	s_cbranch_execz .LBB0_1091
	s_add_u32 s16, s40, 0x4200
	s_addc_u32 s17, s41, 0
	s_mov_b32 s34, 1
	s_mov_b64 s[22:23], 0
	v_mov_b32_e32 v0, 0
	s_branch .LBB0_1082

.LBB0_1196:
	s_or_b64 exec, exec, s[10:11]
	v_cvt_f32_u32_e32 v4, v2
	s_waitcnt vmcnt(0)
	v_readfirstlane_b32 s8, v3
	v_sub_u32_e32 v3, 0, v2
	v_rcp_iflag_f32_e32 v4, v4
	v_add_u32_e32 v5, s8, v1
	v_mul_f32_e32 v4, 0x4f7ffffe, v4
	v_cvt_u32_f32_e32 v4, v4
	v_mul_lo_u32 v1, v3, v4
	v_mul_hi_u32 v1, v4, v1
	v_add_u32_e32 v1, v4, v1
	v_mul_hi_u32 v1, v5, v1
	v_mul_lo_u32 v3, v1, v2
	v_sub_u32_e32 v3, v5, v3
	v_add_u32_e32 v4, 1, v1
	v_cmp_ge_u32_e32 vcc, v3, v2
	s_nop 1
	v_cndmask_b32_e32 v1, v1, v4, vcc
	v_sub_u32_e32 v4, v3, v2
	v_cndmask_b32_e32 v3, v3, v4, vcc
	v_add_u32_e32 v4, 1, v1
	v_cmp_ge_u32_e32 vcc, v3, v2
	v_add_u32_e32 v3, 1, v5
	s_nop 0
	v_cndmask_b32_e32 v1, v1, v4, vcc
	v_mul_lo_u32 v4, v2, v1
	v_add_u32_e32 v2, v4, v2
	v_cmp_ne_u32_e32 vcc, v3, v2
	s_and_saveexec_b64 s[8:9], vcc
	s_xor_b64 s[8:9], exec, s[8:9]
	s_cbranch_execz .LBB0_1210
	s_waitcnt lgkmcnt(0)
	buffer_inv sc1
	v_mov_b32_e32 v0, 0x7500
	global_load_dword v0, v0, s[40:41] sc1
	s_add_u32 s16, s40, 0x7500
	s_addc_u32 s17, s41, 0
	s_waitcnt vmcnt(0)
	v_cmp_eq_u32_e32 vcc, v0, v1
	s_and_saveexec_b64 s[10:11], vcc
	s_cbranch_execz .LBB0_1209
	s_add_u32 s14, s40, 0x4200
	s_addc_u32 s15, s41, 0
	s_mov_b32 s30, 1
	s_mov_b64 s[20:21], 0
	v_mov_b32_e32 v0, 0
	s_branch .LBB0_1200

.LBB0_1305:
	s_or_b64 exec, exec, s[10:11]
	v_cvt_f32_u32_e32 v4, v2
	s_waitcnt vmcnt(0)
	v_readfirstlane_b32 s3, v3
	v_sub_u32_e32 v3, 0, v2
	v_rcp_iflag_f32_e32 v4, v4
	v_add_u32_e32 v5, s3, v1
	v_mul_f32_e32 v4, 0x4f7ffffe, v4
	v_cvt_u32_f32_e32 v4, v4
	v_mul_lo_u32 v1, v3, v4
	v_mul_hi_u32 v1, v4, v1
	v_add_u32_e32 v1, v4, v1
	v_mul_hi_u32 v1, v5, v1
	v_mul_lo_u32 v3, v1, v2
	v_sub_u32_e32 v3, v5, v3
	v_add_u32_e32 v4, 1, v1
	v_cmp_ge_u32_e32 vcc, v3, v2
	s_nop 1
	v_cndmask_b32_e32 v1, v1, v4, vcc
	v_sub_u32_e32 v4, v3, v2
	v_cndmask_b32_e32 v3, v3, v4, vcc
	v_add_u32_e32 v4, 1, v1
	v_cmp_ge_u32_e32 vcc, v3, v2
	v_add_u32_e32 v3, 1, v5
	s_nop 0
	v_cndmask_b32_e32 v1, v1, v4, vcc
	v_mul_lo_u32 v4, v2, v1
	v_add_u32_e32 v2, v4, v2
	v_cmp_ne_u32_e32 vcc, v3, v2
	s_and_saveexec_b64 s[8:9], vcc
	s_xor_b64 s[8:9], exec, s[8:9]
	s_cbranch_execz .LBB0_1319
	s_waitcnt lgkmcnt(0)
	buffer_inv sc1
	v_mov_b32_e32 v0, 0x7500
	global_load_dword v0, v0, s[40:41] sc1
	s_add_u32 s14, s40, 0x7500
	s_addc_u32 s15, s41, 0
	s_waitcnt vmcnt(0)
	v_cmp_eq_u32_e32 vcc, v0, v1
	s_and_saveexec_b64 s[10:11], vcc
	s_cbranch_execz .LBB0_1318
	s_add_u32 s12, s40, 0x4200
	s_addc_u32 s13, s41, 0
	s_mov_b32 s3, 1
	s_mov_b64 s[16:17], 0
	v_mov_b32_e32 v0, 0
	s_branch .LBB0_1309
